# P2 carry-in fold: batched LDS reads instead of serialized branch chain
# speedup vs baseline: 1.0088x; 1.0088x over previous
.LBB0_217:
	s_or_b64 exec, exec, s[6:7]
	s_waitcnt lgkmcnt(2)
	v_lshlrev_b32_e32 v2, 3, v88
	v_readlane_b32 s6, v255, 10
	v_add_u32_e32 v30, v56, v2
	v_add_u32_e32 v2, 0x1c00, v30
	v_or_b32_e32 v21, s6, v54
	s_add_u32 s6, s39, s54
	s_addc_u32 s7, s78, s55
	v_lshl_add_u64 v[22:23], s[6:7], 0, v[2:3]
	v_add_u32_e32 v2, 0x1400, v30
	v_add_co_u32_e32 v22, vcc, s63, v22
	v_lshl_add_u64 v[24:25], s[6:7], 0, v[2:3]
	s_nop 0
	v_addc_co_u32_e32 v23, vcc, 0, v23, vcc
	v_add_co_u32_e32 v24, vcc, s63, v24
	v_add_u32_e32 v2, 0x1420, v30
	s_nop 0
	v_addc_co_u32_e32 v25, vcc, 0, v25, vcc
	v_lshl_add_u64 v[26:27], s[6:7], 0, v[2:3]
	v_add_co_u32_e32 v26, vcc, s63, v26
	v_add_u32_e32 v2, 0x1440, v30
	s_nop 0
	v_addc_co_u32_e32 v27, vcc, 0, v27, vcc
	v_lshl_add_u64 v[28:29], s[6:7], 0, v[2:3]
	s_waitcnt lgkmcnt(0)
	s_barrier
	v_add_co_u32_e32 v28, vcc, s63, v28
	v_add_u32_e32 v2, 0x1460, v30
	v_mul_lo_u32 v20, v55, s60
	v_addc_co_u32_e32 v29, vcc, 0, v29, vcc
	global_load_dwordx2 v[68:69], v[22:23], off
	global_load_dwordx2 v[62:63], v[22:23], off offset:32
	global_load_dwordx2 v[56:57], v[22:23], off offset:64
	global_load_dwordx2 v[48:49], v[22:23], off offset:96
	global_load_dwordx2 v[70:71], v[22:23], off offset:2048
	global_load_dwordx2 v[64:65], v[22:23], off offset:2080
	global_load_dwordx2 v[58:59], v[22:23], off offset:2112
	global_load_dwordx2 v[50:51], v[22:23], off offset:2144
	v_lshl_add_u64 v[22:23], s[6:7], 0, v[2:3]
	v_add_lshl_u32 v20, v21, v20, 1
	v_add_co_u32_e32 v22, vcc, s63, v22
	v_mov_b32_e32 v21, v3
	s_nop 0
	v_addc_co_u32_e32 v23, vcc, 0, v23, vcc
	v_lshl_add_u64 v[20:21], s[6:7], 0, v[20:21]
	s_mov_b32 s6, 0x9f57000
	global_load_dwordx2 v[72:73], v[24:25], off
	global_load_dwordx2 v[66:67], v[26:27], off
	global_load_dwordx2 v[60:61], v[28:29], off
	global_load_dwordx2 v[54:55], v[22:23], off
	v_add_co_u32_e32 v22, vcc, s6, v20
	s_mov_b32 s6, 0x9f5a000
	s_nop 0
	v_addc_co_u32_e32 v23, vcc, 0, v21, vcc
	v_add_co_u32_e32 v24, vcc, s6, v20
	s_mov_b32 s6, 0x9f5d000
	s_nop 0
	v_addc_co_u32_e32 v25, vcc, 0, v21, vcc
	global_load_dwordx4 v[28:31], v[22:23], off offset:3072
	s_nop 0
	global_load_dwordx4 v[24:27], v[24:25], off offset:2048
	v_add_co_u32_e32 v22, vcc, s6, v20
	s_lshl_b32 s6, s41, 8
	s_nop 0
	v_addc_co_u32_e32 v23, vcc, 0, v21, vcc
	v_add_co_u32_e32 v32, vcc, s66, v20
	s_add_i32 s6, s6, 0
	s_nop 0
	v_addc_co_u32_e32 v33, vcc, 0, v21, vcc
	v_add_co_u32_e32 v20, vcc, 0x9f62000, v20
	global_load_dwordx4 v[36:39], v[22:23], off offset:1024
	s_nop 0
	global_load_dwordx4 v[32:35], v[32:33], off
	v_addc_co_u32_e32 v21, vcc, 0, v21, vcc
	global_load_dwordx4 v[20:23], v[20:21], off offset:3072
	v_cmp_lt_u32_e64 s[20:21], 1, v88
	v_cmp_eq_u32_e64 s[22:23], 3, v88
	v_add_u32_e32 v2, s6, v89
	v_add_u32_e32 v2, 0x20800, v2
	v_add_u32_e32 v238, 0x1f800, v89
	ds_read_b32 v216, v2
	ds_read_b32 v217, v2 offset:64
	ds_read_b32 v218, v2 offset:128
	ds_read_b32 v219, v2 offset:192
	v_add_u32_e32 v239, 64, v238
	v_add_u32_e32 v240, 0x80, v238
	v_add_u32_e32 v241, 0xc0, v238
	ds_read2st64_b32 v[160:161], v238 offset1:8
	ds_read2st64_b32 v[174:175], v239 offset1:8
	ds_read2st64_b32 v[188:189], v240 offset1:8
	ds_read2st64_b32 v[202:203], v241 offset1:8
	ds_read2st64_b32 v[162:163], v238 offset0:1 offset1:9
	ds_read2st64_b32 v[176:177], v239 offset0:1 offset1:9
	ds_read2st64_b32 v[190:191], v240 offset0:1 offset1:9
	ds_read2st64_b32 v[204:205], v241 offset0:1 offset1:9
	ds_read2st64_b32 v[164:165], v238 offset0:2 offset1:10
	ds_read2st64_b32 v[178:179], v239 offset0:2 offset1:10
	ds_read2st64_b32 v[192:193], v240 offset0:2 offset1:10
	ds_read2st64_b32 v[206:207], v241 offset0:2 offset1:10
	ds_read2st64_b32 v[166:167], v238 offset0:3 offset1:11
	ds_read2st64_b32 v[180:181], v239 offset0:3 offset1:11
	ds_read2st64_b32 v[194:195], v240 offset0:3 offset1:11
	ds_read2st64_b32 v[208:209], v241 offset0:3 offset1:11
	ds_read2st64_b32 v[168:169], v238 offset0:4 offset1:12
	ds_read2st64_b32 v[182:183], v239 offset0:4 offset1:12
	ds_read2st64_b32 v[196:197], v240 offset0:4 offset1:12
	ds_read2st64_b32 v[210:211], v241 offset0:4 offset1:12
	ds_read2st64_b32 v[170:171], v238 offset0:5 offset1:13
	ds_read2st64_b32 v[184:185], v239 offset0:5 offset1:13
	ds_read2st64_b32 v[198:199], v240 offset0:5 offset1:13
	ds_read2st64_b32 v[212:213], v241 offset0:5 offset1:13
	ds_read2st64_b32 v[172:173], v238 offset0:6 offset1:14
	ds_read2st64_b32 v[186:187], v239 offset0:6 offset1:14
	ds_read2st64_b32 v[200:201], v240 offset0:6 offset1:14
	ds_read2st64_b32 v[214:215], v241 offset0:6 offset1:14
	ds_read2_b32 v[220:221], v106 offset1:68
	ds_read2_b32 v[222:223], v106 offset0:136 offset1:204
	ds_read2_b32 v[224:225], v106 offset0:16 offset1:84
	ds_read2_b32 v[226:227], v106 offset0:152 offset1:220
	ds_read2_b32 v[230:231], v106 offset0:32 offset1:100
	ds_read2_b32 v[232:233], v106 offset0:168 offset1:236
	ds_read2_b32 v[234:235], v106 offset0:48 offset1:116
	ds_read2_b32 v[236:237], v106 offset0:184 offset1:252
	s_xor_b32 s96, s41, 1
	v_readlane_b32 s56, v255, 17
	v_readlane_b32 s57, v255, 18
	s_lshl_b32 s58, s96, 8
	s_add_i32 s58, s58, 0x20800
	v_add_u32_e32 v245, s58, v89
	s_and_b64 s[56:57], s[56:57], s[22:23]
	v_cndmask_b32_e64 v246, v136, 0, s[0:1]
	v_cndmask_b32_e64 v247, v122, 1.0, s[0:1]
	v_fmac_f32_e32 v132, v246, v123
	v_mul_f32_e32 v244, v247, v123
	v_cndmask_b32_e64 v246, v246, v132, s[20:21]
	v_cndmask_b32_e64 v247, v247, v244, s[20:21]
	v_fmac_f32_e32 v131, v246, v120
	v_mul_f32_e32 v244, v247, v120
	v_cndmask_b32_e64 v246, v246, v131, s[22:23]
	v_cndmask_b32_e64 v247, v247, v244, s[22:23]
	v_cndmask_b32_e64 v248, v130, 0, s[0:1]
	v_cndmask_b32_e64 v249, v126, 1.0, s[0:1]
	v_fmac_f32_e32 v129, v248, v128
	v_mul_f32_e32 v244, v249, v128
	v_cndmask_b32_e64 v248, v248, v129, s[20:21]
	v_cndmask_b32_e64 v249, v249, v244, s[20:21]
	v_fmac_f32_e32 v125, v248, v124
	v_mul_f32_e32 v244, v249, v124
	v_cndmask_b32_e64 v248, v248, v125, s[22:23]
	v_cndmask_b32_e64 v249, v249, v244, s[22:23]
	v_cndmask_b32_e64 v250, v139, 0, s[0:1]
	v_cndmask_b32_e64 v251, v135, 1.0, s[0:1]
	v_fmac_f32_e32 v138, v250, v137
	v_mul_f32_e32 v244, v251, v137
	v_cndmask_b32_e64 v250, v250, v138, s[20:21]
	v_cndmask_b32_e64 v251, v251, v244, s[20:21]
	v_fmac_f32_e32 v134, v250, v133
	v_mul_f32_e32 v244, v251, v133
	v_cndmask_b32_e64 v250, v250, v134, s[22:23]
	v_cndmask_b32_e64 v251, v251, v244, s[22:23]
	v_cndmask_b32_e64 v252, v146, 0, s[0:1]
	v_cndmask_b32_e64 v253, v142, 1.0, s[0:1]
	v_fmac_f32_e32 v145, v252, v143
	v_mul_f32_e32 v244, v253, v143
	v_cndmask_b32_e64 v252, v252, v145, s[20:21]
	v_cndmask_b32_e64 v253, v253, v244, s[20:21]
	v_fmac_f32_e32 v141, v252, v140
	v_mul_f32_e32 v244, v253, v140
	v_cndmask_b32_e64 v252, v252, v141, s[22:23]
	v_cndmask_b32_e64 v253, v253, v244, s[22:23]
	s_waitcnt lgkmcnt(15)
	s_andn2_b64 vcc, exec, s[82:83]
	s_cbranch_vccnz .Lb4_fold_done
	v_fma_f32 v216, v160, v216, v161
	v_fma_f32 v217, v174, v217, v175
	v_fma_f32 v218, v188, v218, v189
	v_fma_f32 v219, v202, v219, v203
	s_andn2_b64 vcc, exec, s[84:85]
	s_cbranch_vccnz .Lb4_fold_done
	v_fma_f32 v216, v162, v216, v163
	v_fma_f32 v217, v176, v217, v177
	v_fma_f32 v218, v190, v218, v191
	v_fma_f32 v219, v204, v219, v205
	s_andn2_b64 vcc, exec, s[86:87]
	s_cbranch_vccnz .Lb4_fold_done
	v_fma_f32 v216, v164, v216, v165
	v_fma_f32 v217, v178, v217, v179
	v_fma_f32 v218, v192, v218, v193
	v_fma_f32 v219, v206, v219, v207
	s_andn2_b64 vcc, exec, s[88:89]
	s_cbranch_vccnz .Lb4_fold_done
	v_fma_f32 v216, v166, v216, v167
	v_fma_f32 v217, v180, v217, v181
	v_fma_f32 v218, v194, v218, v195
	v_fma_f32 v219, v208, v219, v209
	s_andn2_b64 vcc, exec, s[90:91]
	s_cbranch_vccnz .Lb4_fold_done
	v_fma_f32 v216, v168, v216, v169
	v_fma_f32 v217, v182, v217, v183
	v_fma_f32 v218, v196, v218, v197
	v_fma_f32 v219, v210, v219, v211
	s_waitcnt lgkmcnt(8)
	s_andn2_b64 vcc, exec, s[92:93]
	s_cbranch_vccnz .Lb4_fold_done
	v_fma_f32 v216, v170, v216, v171
	v_fma_f32 v217, v184, v217, v185
	v_fma_f32 v218, v198, v218, v199
	v_fma_f32 v219, v212, v219, v213
	s_andn2_b64 vcc, exec, s[94:95]
	s_cbranch_vccnz .Lb4_fold_done
	v_fma_f32 v216, v172, v216, v173
	v_fma_f32 v217, v186, v217, v187
	v_fma_f32 v218, v200, v218, v201
	v_fma_f32 v219, v214, v219, v215
.Lb4_fold_done:
	v_fmac_f32_e32 v246, v247, v216
	v_fmac_f32_e32 v248, v249, v217
	v_fmac_f32_e32 v250, v251, v218
	v_fmac_f32_e32 v252, v253, v219
	s_waitcnt lgkmcnt(0)
	v_fma_f32 v220, v74, v246, v220
	v_fmac_f32_e32 v221, v75, v220
	v_fma_f32 v222, v0, v221, v222
	v_fmac_f32_e32 v223, v1, v222
	v_fma_f32 v224, v78, v248, v224
	v_fmac_f32_e32 v225, v79, v224
	v_fma_f32 v226, v76, v225, v226
	v_fmac_f32_e32 v227, v77, v226
	v_fma_f32 v230, v82, v250, v230
	v_fmac_f32_e32 v231, v83, v230
	v_fma_f32 v232, v80, v231, v232
	v_fmac_f32_e32 v233, v81, v232
	v_fma_f32 v234, v86, v252, v234
	v_fmac_f32_e32 v235, v87, v234
	v_fma_f32 v236, v84, v235, v236
	v_fmac_f32_e32 v237, v85, v236
	ds_write2_b32 v106, v220, v221 offset1:68
	ds_write2_b32 v106, v222, v223 offset0:136 offset1:204
	ds_write2_b32 v106, v224, v225 offset0:16 offset1:84
	ds_write2_b32 v106, v226, v227 offset0:152 offset1:220
	ds_write2_b32 v106, v230, v231 offset0:32 offset1:100
	ds_write2_b32 v106, v232, v233 offset0:168 offset1:236
	ds_write2_b32 v106, v234, v235 offset0:48 offset1:116
	ds_write2_b32 v106, v236, v237 offset0:184 offset1:252
	s_and_saveexec_b64 s[58:59], s[56:57]
	ds_write_b32 v245, v223
	ds_write_b32 v245, v227 offset:64
	ds_write_b32 v245, v233 offset:128
	ds_write_b32 v245, v237 offset:192
	s_or_b64 exec, exec, s[58:59]
	s_mov_b64 s[0:1], exec
	s_branch .LBB0_208
